# v63 + 32 bytes of unreachable padding before the attention loops (placement shift, byte phase mod 8 unchanged)
# baseline (speedup 1.0000x reference)
.LBB0_381:
	v_lshrrev_b32_e32 v0, 2, v81
	v_exp_f32_e32 v3, v84
	v_exp_f32_e32 v7, v83
	v_exp_f32_e32 v6, v49
	v_exp_f32_e32 v11, v48
	v_exp_f32_e32 v10, v51
	v_exp_f32_e32 v96, v50
	v_exp_f32_e32 v15, v53
	v_exp_f32_e32 v97, v52
	v_exp_f32_e32 v2, v55
	v_exp_f32_e32 v5, v54
	v_exp_f32_e32 v4, v57
	v_exp_f32_e32 v9, v56
	v_exp_f32_e32 v8, v59
	v_exp_f32_e32 v12, v58
	v_exp_f32_e32 v13, v61
	v_exp_f32_e32 v14, v60
	s_min_i32 s2, s29, 26
	v_and_or_b32 v0, v0, 3, v158
	v_lshlrev_b32_e32 v62, 1, v81
	s_sub_i32 s54, s2, s5
	v_lshlrev_b32_e32 v0, 6, v0
	v_and_b32_e32 v48, 32, v62
	v_mov_b32_e32 v155, v154
	s_mov_b32 s29, 1
	s_cmp_lt_i32 s54, -5
	v_or3_b32 v0, v48, v0, v82
	s_cbranch_scc1 .LBB0_391
	v_lshl_or_b32 v48, s5, 6, v158
	v_sub_u32_e32 v48, v48, v80
	v_subrev_u32_e32 v48, s53, v48
	s_lshl_b32 s2, s30, 8
	v_subrev_u32_e32 v162, s2, v48
	v_mov_b64_e32 v[62:63], v[46:47]
	s_add_i32 s54, s54, 8
	s_mov_b32 s30, 0x8000
	s_movk_i32 s53, 0x4000
	s_mov_b32 s2, 0
	s_mov_b32 s29, 3
	v_mov_b64_e32 v[60:61], v[44:45]
	v_mov_b64_e32 v[58:59], v[42:43]
	v_mov_b64_e32 v[56:57], v[40:41]
	v_mov_b64_e32 v[54:55], v[38:39]
	v_mov_b64_e32 v[52:53], v[36:37]
	v_mov_b64_e32 v[50:51], v[34:35]
	v_mov_b64_e32 v[48:49], v[32:33]
	s_branch .LBB0_383
	s_nop 0
	s_nop 0
	s_nop 0
	s_nop 0
	s_nop 0
	s_nop 0
	s_nop 0
	s_nop 0
